# E7: drop redundant acquire-invalidate in the 8 in-phase row-stat exchanges (sc1 stores + sc1 loads both sides); on E1+E2+E5
# speedup vs baseline: 1.0255x; 1.0072x over previous
.LBB0_653:
.LBB0_654:
	s_or_b64 exec, exec, s[34:35]
	s_waitcnt vmcnt(0) lgkmcnt(0)
	s_barrier
	s_and_saveexec_b64 s[34:35], s[6:7]
	s_cbranch_execz .LBB0_656
	v_lshlrev_b64 v[12:13], 7, v[12:13]
	v_lshl_add_u64 v[12:13], s[18:19], 0, v[12:13]
	global_load_dword v16, v[12:13], off sc1
	global_load_dword v17, v[12:13], off offset:4 sc1
	global_load_dword v18, v[12:13], off offset:8 sc1
	global_load_dword v19, v[12:13], off offset:12 sc1
	global_load_dword v20, v[12:13], off offset:16 sc1
	global_load_dword v21, v[12:13], off offset:20 sc1
	global_load_dword v22, v[12:13], off offset:24 sc1
	global_load_dword v23, v[12:13], off offset:28 sc1
	global_load_dword v24, v[12:13], off offset:32 sc1
	global_load_dword v25, v[12:13], off offset:36 sc1
	global_load_dword v26, v[12:13], off offset:40 sc1
	global_load_dword v27, v[12:13], off offset:44 sc1
	global_load_dword v28, v[12:13], off offset:48 sc1
	global_load_dword v29, v[12:13], off offset:52 sc1
	global_load_dword v30, v[12:13], off offset:56 sc1
	global_load_dword v31, v[12:13], off offset:60 sc1
	global_load_dword v32, v[12:13], off offset:64 sc1
	global_load_dword v33, v[12:13], off offset:68 sc1
	global_load_dword v34, v[12:13], off offset:72 sc1
	global_load_dword v35, v[12:13], off offset:76 sc1
	global_load_dword v36, v[12:13], off offset:80 sc1
	global_load_dword v37, v[12:13], off offset:84 sc1
	global_load_dword v38, v[12:13], off offset:88 sc1
	global_load_dword v39, v[12:13], off offset:92 sc1
	global_load_dword v40, v[12:13], off offset:96 sc1
	global_load_dword v41, v[12:13], off offset:100 sc1
	global_load_dword v42, v[12:13], off offset:104 sc1
	global_load_dword v43, v[12:13], off offset:108 sc1
	global_load_dword v44, v[12:13], off offset:112 sc1
	global_load_dword v45, v[12:13], off offset:116 sc1
	global_load_dword v46, v[12:13], off offset:120 sc1
	s_nop 0
	global_load_dword v12, v[12:13], off offset:124 sc1
	s_waitcnt vmcnt(31)
	v_add_f32_e32 v13, 0, v16
	s_waitcnt vmcnt(30)
	v_add_f32_e32 v13, v13, v17
	s_waitcnt vmcnt(29)
	v_add_f32_e32 v13, v13, v18
	s_waitcnt vmcnt(28)
	v_add_f32_e32 v13, v13, v19
	s_waitcnt vmcnt(27)
	v_add_f32_e32 v13, v13, v20
	s_waitcnt vmcnt(26)
	v_add_f32_e32 v13, v13, v21
	s_waitcnt vmcnt(25)
	v_add_f32_e32 v13, v13, v22
	s_waitcnt vmcnt(24)
	v_add_f32_e32 v13, v13, v23
	s_waitcnt vmcnt(23)
	v_add_f32_e32 v13, v13, v24
	s_waitcnt vmcnt(22)
	v_add_f32_e32 v13, v13, v25
	s_waitcnt vmcnt(21)
	v_add_f32_e32 v13, v13, v26
	s_waitcnt vmcnt(20)
	v_add_f32_e32 v13, v13, v27
	s_waitcnt vmcnt(19)
	v_add_f32_e32 v13, v13, v28
	s_waitcnt vmcnt(18)
	v_add_f32_e32 v13, v13, v29
	s_waitcnt vmcnt(17)
	v_add_f32_e32 v13, v13, v30
	s_waitcnt vmcnt(16)
	v_add_f32_e32 v13, v13, v31
	s_waitcnt vmcnt(15)
	v_add_f32_e32 v13, v13, v32
	s_waitcnt vmcnt(14)
	v_add_f32_e32 v13, v13, v33
	s_waitcnt vmcnt(13)
	v_add_f32_e32 v13, v13, v34
	s_waitcnt vmcnt(12)
	v_add_f32_e32 v13, v13, v35
	s_waitcnt vmcnt(11)
	v_add_f32_e32 v13, v13, v36
	s_waitcnt vmcnt(10)
	v_add_f32_e32 v13, v13, v37
	s_waitcnt vmcnt(9)
	v_add_f32_e32 v13, v13, v38
	s_waitcnt vmcnt(8)
	v_add_f32_e32 v13, v13, v39
	s_waitcnt vmcnt(7)
	v_add_f32_e32 v13, v13, v40
	s_waitcnt vmcnt(6)
	v_add_f32_e32 v13, v13, v41
	s_waitcnt vmcnt(5)
	v_add_f32_e32 v13, v13, v42
	s_waitcnt vmcnt(4)
	v_add_f32_e32 v13, v13, v43
	s_waitcnt vmcnt(3)
	v_add_f32_e32 v13, v13, v44
	s_waitcnt vmcnt(2)
	v_add_f32_e32 v13, v13, v45
	s_waitcnt vmcnt(1)
	v_add_f32_e32 v13, v13, v46
	s_waitcnt vmcnt(0)
	v_add_f32_e32 v12, v13, v12
	ds_write_b32 v15, v12 offset:1536

.LBB0_710:
.LBB0_711:
	s_waitcnt vmcnt(0) lgkmcnt(0)
	s_barrier
	s_lshl_b32 s3, s12, 8
	s_and_saveexec_b64 s[12:13], s[4:5]
	s_cbranch_execz .LBB0_713
	v_add_u32_e32 v134, s3, v132
	v_ashrrev_i32_e32 v135, 31, v134
	v_lshl_add_u64 v[134:135], v[134:135], 4, s[16:17]
	s_waitcnt lgkmcnt(0)
	global_load_dword v133, v[134:135], off sc1
	global_load_dword v136, v[134:135], off offset:4 sc1
	global_load_dword v137, v[134:135], off offset:8 sc1
	s_nop 0
	global_load_dword v134, v[134:135], off offset:12 sc1
	v_mov_b32_e32 v135, 0x358637bd
	s_mov_b32 s4, 0xf800000
	v_lshl_add_u32 v132, v132, 2, 0
	s_waitcnt vmcnt(0)
	v_add_f32_e32 v133, 0, v133
	v_add_f32_e32 v133, v133, v136
	v_add_f32_e32 v133, v133, v137
	v_add_f32_e32 v133, v133, v134
	v_fmac_f32_e32 v135, 0x3a800000, v133
	v_mul_f32_e32 v133, 0x4f800000, v135
	v_cmp_gt_f32_e32 vcc, s4, v135
	s_nop 1
	v_cndmask_b32_e32 v133, v135, v133, vcc
	v_sqrt_f32_e32 v134, v133
	v_mov_b32_e32 v135, 0x260
	v_add_u32_e32 v136, -1, v134
	v_add_u32_e32 v137, 1, v134
	v_fma_f32 v138, -v136, v134, v133
	v_fma_f32 v139, -v137, v134, v133
	v_cmp_ge_f32_e64 s[4:5], 0, v138
	s_nop 1
	v_cndmask_b32_e64 v134, v134, v136, s[4:5]
	v_cmp_lt_f32_e64 s[4:5], 0, v139
	s_nop 1
	v_cndmask_b32_e64 v134, v134, v137, s[4:5]
	v_mul_f32_e32 v136, 0x37800000, v134
	v_cndmask_b32_e32 v134, v134, v136, vcc
	v_cmp_class_f32_e32 vcc, v133, v135
	s_nop 1
	v_cndmask_b32_e32 v133, v134, v133, vcc
	v_div_scale_f32 v134, s[4:5], v133, v133, 1.0
	v_rcp_f32_e32 v135, v134
	v_div_scale_f32 v136, vcc, 1.0, v133, 1.0
	v_fma_f32 v137, -v134, v135, 1.0
	v_fmac_f32_e32 v135, v137, v135
	v_mul_f32_e32 v137, v136, v135
	v_fma_f32 v138, -v134, v137, v136
	v_fmac_f32_e32 v137, v138, v135
	v_fma_f32 v134, -v134, v137, v136
	v_div_fmas_f32 v134, v134, v135, v137
	v_div_fixup_f32 v133, v134, v133, 1.0
	ds_write_b32 v132, v133 offset:4096

.LBB0_967:
.LBB0_968:
	s_waitcnt vmcnt(0) lgkmcnt(0)
	s_barrier
	s_and_saveexec_b64 s[16:17], s[4:5]
	s_cbranch_execz .LBB0_970
	v_lshl_add_u64 v[164:165], v[164:165], 4, s[10:11]
	global_load_dword v167, v[164:165], off sc1
	global_load_dword v168, v[164:165], off offset:4 sc1
	global_load_dword v169, v[164:165], off offset:8 sc1
	s_nop 0
	global_load_dword v164, v[164:165], off offset:12 sc1
	v_mov_b32_e32 v165, 0x358637bd
	s_mov_b32 s3, 0xf800000
	s_waitcnt vmcnt(0)
	v_add_f32_e32 v167, 0, v167
	v_add_f32_e32 v167, v167, v168
	v_add_f32_e32 v167, v167, v169
	v_add_f32_e32 v164, v167, v164
	v_fmac_f32_e32 v165, 0x3a800000, v164
	v_mul_f32_e32 v164, 0x4f800000, v165
	v_cmp_gt_f32_e32 vcc, s3, v165
	v_mov_b32_e32 v167, 0x260
	s_nop 0
	v_cndmask_b32_e32 v164, v165, v164, vcc
	v_sqrt_f32_e32 v165, v164
	s_nop 0
	v_add_u32_e32 v168, -1, v165
	v_add_u32_e32 v169, 1, v165
	v_fma_f32 v170, -v168, v165, v164
	v_fma_f32 v171, -v169, v165, v164
	v_cmp_ge_f32_e64 s[4:5], 0, v170
	s_nop 1
	v_cndmask_b32_e64 v165, v165, v168, s[4:5]
	v_cmp_lt_f32_e64 s[4:5], 0, v171
	s_nop 1
	v_cndmask_b32_e64 v165, v165, v169, s[4:5]
	v_mul_f32_e32 v168, 0x37800000, v165
	v_cndmask_b32_e32 v165, v165, v168, vcc
	v_cmp_class_f32_e32 vcc, v164, v167
	s_nop 1
	v_cndmask_b32_e32 v164, v165, v164, vcc
	v_div_scale_f32 v165, s[4:5], v164, v164, 1.0
	v_rcp_f32_e32 v167, v165
	v_div_scale_f32 v168, vcc, 1.0, v164, 1.0
	v_fma_f32 v169, -v165, v167, 1.0
	v_fmac_f32_e32 v167, v169, v167
	v_mul_f32_e32 v169, v168, v167
	v_fma_f32 v170, -v165, v169, v168
	v_fmac_f32_e32 v169, v170, v167
	v_fma_f32 v165, -v165, v169, v168
	v_div_fmas_f32 v165, v165, v167, v169
	v_div_fixup_f32 v164, v165, v164, 1.0
	v_lshl_add_u32 v165, v166, 2, 0
	ds_write_b32 v165, v164 offset:4096

.LBB0_1586:
.LBB0_1587:
	s_or_b64 exec, exec, s[34:35]
	s_waitcnt vmcnt(0) lgkmcnt(0)
	s_barrier
	s_and_saveexec_b64 s[34:35], s[6:7]
	s_cbranch_execz .LBB0_1589
	v_lshlrev_b64 v[10:11], 7, v[10:11]
	v_lshl_add_u64 v[10:11], s[16:17], 0, v[10:11]
	global_load_dword v14, v[10:11], off sc1
	global_load_dword v15, v[10:11], off offset:4 sc1
	global_load_dword v16, v[10:11], off offset:8 sc1
	global_load_dword v17, v[10:11], off offset:12 sc1
	global_load_dword v18, v[10:11], off offset:16 sc1
	global_load_dword v19, v[10:11], off offset:20 sc1
	global_load_dword v20, v[10:11], off offset:24 sc1
	global_load_dword v21, v[10:11], off offset:28 sc1
	global_load_dword v22, v[10:11], off offset:32 sc1
	global_load_dword v23, v[10:11], off offset:36 sc1
	global_load_dword v24, v[10:11], off offset:40 sc1
	global_load_dword v25, v[10:11], off offset:44 sc1
	global_load_dword v26, v[10:11], off offset:48 sc1
	global_load_dword v27, v[10:11], off offset:52 sc1
	global_load_dword v28, v[10:11], off offset:56 sc1
	global_load_dword v29, v[10:11], off offset:60 sc1
	global_load_dword v30, v[10:11], off offset:64 sc1
	global_load_dword v31, v[10:11], off offset:68 sc1
	global_load_dword v32, v[10:11], off offset:72 sc1
	global_load_dword v33, v[10:11], off offset:76 sc1
	global_load_dword v34, v[10:11], off offset:80 sc1
	global_load_dword v35, v[10:11], off offset:84 sc1
	global_load_dword v36, v[10:11], off offset:88 sc1
	global_load_dword v37, v[10:11], off offset:92 sc1
	global_load_dword v38, v[10:11], off offset:96 sc1
	global_load_dword v39, v[10:11], off offset:100 sc1
	global_load_dword v40, v[10:11], off offset:104 sc1
	global_load_dword v41, v[10:11], off offset:108 sc1
	global_load_dword v42, v[10:11], off offset:112 sc1
	global_load_dword v43, v[10:11], off offset:116 sc1
	global_load_dword v44, v[10:11], off offset:120 sc1
	s_nop 0
	global_load_dword v10, v[10:11], off offset:124 sc1
	s_waitcnt vmcnt(31)
	v_add_f32_e32 v11, 0, v14
	s_waitcnt vmcnt(30)
	v_add_f32_e32 v11, v11, v15
	s_waitcnt vmcnt(29)
	v_add_f32_e32 v11, v11, v16
	s_waitcnt vmcnt(28)
	v_add_f32_e32 v11, v11, v17
	s_waitcnt vmcnt(27)
	v_add_f32_e32 v11, v11, v18
	s_waitcnt vmcnt(26)
	v_add_f32_e32 v11, v11, v19
	s_waitcnt vmcnt(25)
	v_add_f32_e32 v11, v11, v20
	s_waitcnt vmcnt(24)
	v_add_f32_e32 v11, v11, v21
	s_waitcnt vmcnt(23)
	v_add_f32_e32 v11, v11, v22
	s_waitcnt vmcnt(22)
	v_add_f32_e32 v11, v11, v23
	s_waitcnt vmcnt(21)
	v_add_f32_e32 v11, v11, v24
	s_waitcnt vmcnt(20)
	v_add_f32_e32 v11, v11, v25
	s_waitcnt vmcnt(19)
	v_add_f32_e32 v11, v11, v26
	s_waitcnt vmcnt(18)
	v_add_f32_e32 v11, v11, v27
	s_waitcnt vmcnt(17)
	v_add_f32_e32 v11, v11, v28
	s_waitcnt vmcnt(16)
	v_add_f32_e32 v11, v11, v29
	s_waitcnt vmcnt(15)
	v_add_f32_e32 v11, v11, v30
	s_waitcnt vmcnt(14)
	v_add_f32_e32 v11, v11, v31
	s_waitcnt vmcnt(13)
	v_add_f32_e32 v11, v11, v32
	s_waitcnt vmcnt(12)
	v_add_f32_e32 v11, v11, v33
	s_waitcnt vmcnt(11)
	v_add_f32_e32 v11, v11, v34
	s_waitcnt vmcnt(10)
	v_add_f32_e32 v11, v11, v35
	s_waitcnt vmcnt(9)
	v_add_f32_e32 v11, v11, v36
	s_waitcnt vmcnt(8)
	v_add_f32_e32 v11, v11, v37
	s_waitcnt vmcnt(7)
	v_add_f32_e32 v11, v11, v38
	s_waitcnt vmcnt(6)
	v_add_f32_e32 v11, v11, v39
	s_waitcnt vmcnt(5)
	v_add_f32_e32 v11, v11, v40
	s_waitcnt vmcnt(4)
	v_add_f32_e32 v11, v11, v41
	s_waitcnt vmcnt(3)
	v_add_f32_e32 v11, v11, v42
	s_waitcnt vmcnt(2)
	v_add_f32_e32 v11, v11, v43
	s_waitcnt vmcnt(1)
	v_add_f32_e32 v11, v11, v44
	s_waitcnt vmcnt(0)
	v_add_f32_e32 v10, v11, v10
	ds_write_b32 v13, v10 offset:1536

.LBB0_1643:
.LBB0_1644:
	s_waitcnt vmcnt(0) lgkmcnt(0)
	s_barrier
	s_and_saveexec_b64 s[12:13], s[4:5]
	s_cbranch_execz .LBB0_1646
	v_lshl_add_u64 v[162:163], v[162:163], 4, s[14:15]
	global_load_dword v165, v[162:163], off sc1
	global_load_dword v166, v[162:163], off offset:4 sc1
	global_load_dword v167, v[162:163], off offset:8 sc1
	s_nop 0
	global_load_dword v162, v[162:163], off offset:12 sc1
	v_mov_b32_e32 v163, 0x358637bd
	s_mov_b32 s3, 0xf800000
	s_waitcnt vmcnt(0)
	v_add_f32_e32 v165, 0, v165
	v_add_f32_e32 v165, v165, v166
	v_add_f32_e32 v165, v165, v167
	v_add_f32_e32 v162, v165, v162
	v_fmac_f32_e32 v163, 0x3a800000, v162
	v_mul_f32_e32 v162, 0x4f800000, v163
	v_cmp_gt_f32_e32 vcc, s3, v163
	v_mov_b32_e32 v165, 0x260
	s_nop 0
	v_cndmask_b32_e32 v162, v163, v162, vcc
	v_sqrt_f32_e32 v163, v162
	s_nop 0
	v_add_u32_e32 v166, -1, v163
	v_add_u32_e32 v167, 1, v163
	v_fma_f32 v168, -v166, v163, v162
	v_fma_f32 v169, -v167, v163, v162
	v_cmp_ge_f32_e64 s[4:5], 0, v168
	s_nop 1
	v_cndmask_b32_e64 v163, v163, v166, s[4:5]
	v_cmp_lt_f32_e64 s[4:5], 0, v169
	s_nop 1
	v_cndmask_b32_e64 v163, v163, v167, s[4:5]
	v_mul_f32_e32 v166, 0x37800000, v163
	v_cndmask_b32_e32 v163, v163, v166, vcc
	v_cmp_class_f32_e32 vcc, v162, v165
	s_nop 1
	v_cndmask_b32_e32 v162, v163, v162, vcc
	v_div_scale_f32 v163, s[4:5], v162, v162, 1.0
	v_rcp_f32_e32 v165, v163
	v_div_scale_f32 v166, vcc, 1.0, v162, 1.0
	v_fma_f32 v167, -v163, v165, 1.0
	v_fmac_f32_e32 v165, v167, v165
	v_mul_f32_e32 v167, v166, v165
	v_fma_f32 v168, -v163, v167, v166
	v_fmac_f32_e32 v167, v168, v165
	v_fma_f32 v163, -v163, v167, v166
	v_div_fmas_f32 v163, v163, v165, v167
	v_div_fixup_f32 v162, v163, v162, 1.0
	v_lshl_add_u32 v163, v164, 2, 0
	ds_write_b32 v163, v162 offset:4096

.LBB0_1839:
.LBB0_1840:
	s_or_b64 exec, exec, s[30:31]
	s_waitcnt vmcnt(0) lgkmcnt(0)
	s_barrier
	s_and_saveexec_b64 s[30:31], s[6:7]
	s_cbranch_execz .LBB0_1819
	v_lshlrev_b64 v[10:11], 7, v[10:11]
	v_lshl_add_u64 v[10:11], s[14:15], 0, v[10:11]
	global_load_dword v13, v[10:11], off sc1
	global_load_dword v14, v[10:11], off offset:4 sc1
	global_load_dword v15, v[10:11], off offset:8 sc1
	global_load_dword v16, v[10:11], off offset:12 sc1
	global_load_dword v17, v[10:11], off offset:16 sc1
	global_load_dword v18, v[10:11], off offset:20 sc1
	global_load_dword v19, v[10:11], off offset:24 sc1
	global_load_dword v20, v[10:11], off offset:28 sc1
	global_load_dword v21, v[10:11], off offset:32 sc1
	global_load_dword v22, v[10:11], off offset:36 sc1
	global_load_dword v23, v[10:11], off offset:40 sc1
	global_load_dword v24, v[10:11], off offset:44 sc1
	global_load_dword v25, v[10:11], off offset:48 sc1
	global_load_dword v26, v[10:11], off offset:52 sc1
	global_load_dword v27, v[10:11], off offset:56 sc1
	global_load_dword v28, v[10:11], off offset:60 sc1
	global_load_dword v29, v[10:11], off offset:64 sc1
	global_load_dword v30, v[10:11], off offset:68 sc1
	global_load_dword v31, v[10:11], off offset:72 sc1
	global_load_dword v32, v[10:11], off offset:76 sc1
	global_load_dword v33, v[10:11], off offset:80 sc1
	global_load_dword v34, v[10:11], off offset:84 sc1
	global_load_dword v35, v[10:11], off offset:88 sc1
	global_load_dword v36, v[10:11], off offset:92 sc1
	global_load_dword v37, v[10:11], off offset:96 sc1
	global_load_dword v38, v[10:11], off offset:100 sc1
	global_load_dword v39, v[10:11], off offset:104 sc1
	global_load_dword v40, v[10:11], off offset:108 sc1
	global_load_dword v41, v[10:11], off offset:112 sc1
	global_load_dword v42, v[10:11], off offset:116 sc1
	global_load_dword v43, v[10:11], off offset:120 sc1
	s_nop 0
	global_load_dword v10, v[10:11], off offset:124 sc1
	s_waitcnt vmcnt(31)
	v_add_f32_e32 v11, 0, v13
	s_waitcnt vmcnt(30)
	v_add_f32_e32 v11, v11, v14
	s_waitcnt vmcnt(29)
	v_add_f32_e32 v11, v11, v15
	s_waitcnt vmcnt(28)
	v_add_f32_e32 v11, v11, v16
	s_waitcnt vmcnt(27)
	v_add_f32_e32 v11, v11, v17
	s_waitcnt vmcnt(26)
	v_add_f32_e32 v11, v11, v18
	s_waitcnt vmcnt(25)
	v_add_f32_e32 v11, v11, v19
	s_waitcnt vmcnt(24)
	v_add_f32_e32 v11, v11, v20
	s_waitcnt vmcnt(23)
	v_add_f32_e32 v11, v11, v21
	s_waitcnt vmcnt(22)
	v_add_f32_e32 v11, v11, v22
	s_waitcnt vmcnt(21)
	v_add_f32_e32 v11, v11, v23
	s_waitcnt vmcnt(20)
	v_add_f32_e32 v11, v11, v24
	s_waitcnt vmcnt(19)
	v_add_f32_e32 v11, v11, v25
	s_waitcnt vmcnt(18)
	v_add_f32_e32 v11, v11, v26
	s_waitcnt vmcnt(17)
	v_add_f32_e32 v11, v11, v27
	s_waitcnt vmcnt(16)
	v_add_f32_e32 v11, v11, v28
	s_waitcnt vmcnt(15)
	v_add_f32_e32 v11, v11, v29
	s_waitcnt vmcnt(14)
	v_add_f32_e32 v11, v11, v30
	s_waitcnt vmcnt(13)
	v_add_f32_e32 v11, v11, v31
	s_waitcnt vmcnt(12)
	v_add_f32_e32 v11, v11, v32
	s_waitcnt vmcnt(11)
	v_add_f32_e32 v11, v11, v33
	s_waitcnt vmcnt(10)
	v_add_f32_e32 v11, v11, v34
	s_waitcnt vmcnt(9)
	v_add_f32_e32 v11, v11, v35
	s_waitcnt vmcnt(8)
	v_add_f32_e32 v11, v11, v36
	s_waitcnt vmcnt(7)
	v_add_f32_e32 v11, v11, v37
	s_waitcnt vmcnt(6)
	v_add_f32_e32 v11, v11, v38
	s_waitcnt vmcnt(5)
	v_add_f32_e32 v11, v11, v39
	s_waitcnt vmcnt(4)
	v_add_f32_e32 v11, v11, v40
	s_waitcnt vmcnt(3)
	v_add_f32_e32 v11, v11, v41
	s_waitcnt vmcnt(2)
	v_add_f32_e32 v11, v11, v42
	s_waitcnt vmcnt(1)
	v_add_f32_e32 v11, v11, v43
	s_waitcnt vmcnt(0)
	v_add_f32_e32 v10, v11, v10
	ds_write_b32 v12, v10 offset:1536
	s_branch .LBB0_1819

.LBB0_1895:
.LBB0_1896:
	s_waitcnt vmcnt(0) lgkmcnt(0)
	s_barrier
	s_and_saveexec_b64 s[4:5], s[0:1]
	s_cbranch_execz .LBB0_1898
	v_lshl_add_u64 v[192:193], v[192:193], 4, s[2:3]
	global_load_dword v195, v[192:193], off sc1
	global_load_dword v196, v[192:193], off offset:4 sc1
	global_load_dword v197, v[192:193], off offset:8 sc1
	s_nop 0
	global_load_dword v192, v[192:193], off offset:12 sc1
	v_mov_b32_e32 v193, 0x358637bd
	s_mov_b32 s0, 0xf800000
	s_waitcnt vmcnt(0)
	v_add_f32_e32 v195, 0, v195
	v_add_f32_e32 v195, v195, v196
	v_add_f32_e32 v195, v195, v197
	v_add_f32_e32 v192, v195, v192
	v_fmac_f32_e32 v193, 0x3a800000, v192
	v_mul_f32_e32 v192, 0x4f800000, v193
	v_cmp_gt_f32_e32 vcc, s0, v193
	v_mov_b32_e32 v195, 0x260
	s_nop 0
	v_cndmask_b32_e32 v192, v193, v192, vcc
	v_sqrt_f32_e32 v193, v192
	s_nop 0
	v_add_u32_e32 v196, -1, v193
	v_add_u32_e32 v197, 1, v193
	v_fma_f32 v202, -v196, v193, v192
	v_fma_f32 v203, -v197, v193, v192
	v_cmp_ge_f32_e64 s[0:1], 0, v202
	s_nop 1
	v_cndmask_b32_e64 v193, v193, v196, s[0:1]
	v_cmp_lt_f32_e64 s[0:1], 0, v203
	s_nop 1
	v_cndmask_b32_e64 v193, v193, v197, s[0:1]
	v_mul_f32_e32 v196, 0x37800000, v193
	v_cndmask_b32_e32 v193, v193, v196, vcc
	v_cmp_class_f32_e32 vcc, v192, v195
	s_nop 1
	v_cndmask_b32_e32 v192, v193, v192, vcc
	v_div_scale_f32 v193, s[0:1], v192, v192, 1.0
	v_rcp_f32_e32 v195, v193
	v_div_scale_f32 v196, vcc, 1.0, v192, 1.0
	v_fma_f32 v197, -v193, v195, 1.0
	v_fmac_f32_e32 v195, v197, v195
	v_mul_f32_e32 v197, v196, v195
	v_fma_f32 v202, -v193, v197, v196
	v_fmac_f32_e32 v197, v202, v195
	v_fma_f32 v193, -v193, v197, v196
	v_div_fmas_f32 v193, v193, v195, v197
	v_div_fixup_f32 v192, v193, v192, 1.0
	v_lshl_add_u32 v193, v194, 2, 0
	ds_write_b32 v193, v192 offset:4096
